# two P2 queues (128 SA-first) + no pool copying in the P2 tail (workgroups go straight to the seam barrier; pool leftovers drain at the end of P3)
# baseline (speedup 1.0000x reference)
.LBB0_599:
	s_load_dwordx16 s[0:15], s[52:53], 0x0
	v_lshlrev_b32_e32 v2, 4, v0
	v_mov_b32_e32 v3, 0
	v_readlane_b32 s48, v248, 40
	s_mov_b64 s[20:21], 0xa000
	s_waitcnt lgkmcnt(0)
	v_lshl_add_u64 v[4:5], s[6:7], 0, v[2:3]
	s_load_dwordx16 s[0:15], s[52:53], 0x40
	s_waitcnt lgkmcnt(0)
	s_mov_b64 s[0:1], 0xa31c000
	s_add_i32 s5, 0, 0x23200
	s_movk_i32 s4, 0x381
	s_mov_b32 s8, 0
	v_lshl_add_u64 v[6:7], s[14:15], 0, v[2:3]
	v_lshl_add_u64 v[6:7], v[6:7], 0, s[0:1]
	v_mov_b32_e32 v1, s5
	s_mov_b64 s[0:1], 0xc000
	s_mov_b64 s[2:3], 0x2000
	s_mov_b64 s[6:7], 0x4000
	s_mov_b64 s[12:13], 0x6000
	s_mov_b64 s[14:15], 0x8000
	s_mov_b64 s[24:25], 0xe000
	s_mov_b64 s[26:27], 0x10000
	v_mov_b32_e32 v2, 0x1800000
	v_readlane_b32 s49, v248, 41
	v_readlane_b32 s50, v248, 42
	v_readlane_b32 s33, v248, 46
	v_readlane_b32 s51, v248, 43
	s_branch .LBB0_609
.LBB0_609:
	s_load_dwordx4 s[28:31], s[52:53], 0x80
	v_readlane_b32 s0, v248, 48
	v_readlane_b32 s1, v248, 49
